# lever 1 (wait placement) in the weight transposes: next round's tile loads are waited for at the register copy at the loop bottom, not right after issue
# baseline (speedup 1.0000x reference)
.Ltr_nonext:
	s_waitcnt lgkmcnt(0)
	s_barrier
	s_waitcnt vmcnt(7)
	ds_write2_b32 v73, v0, v1 offset1:1
	ds_write2_b32 v73, v2, v3 offset0:2 offset1:3
	s_waitcnt vmcnt(6)
	ds_write2_b32 v74, v4, v5 offset1:1
	ds_write2_b32 v74, v6, v7 offset0:2 offset1:3
	v_add_u32_e32 v0, 0x4100, v73
	s_waitcnt vmcnt(5)
	ds_write2_b32 v0, v12, v13 offset1:1
	v_add_u32_e32 v0, 0x4108, v73
	ds_write2_b32 v0, v14, v15 offset1:1
	v_add_u32_e32 v0, 0x4100, v74
	s_waitcnt vmcnt(4)
	ds_write2_b32 v0, v8, v9 offset1:1
	v_add_u32_e32 v0, 0x4108, v74
	ds_write2_b32 v0, v10, v11 offset1:1
	v_add_u32_e32 v0, 0x8200, v73
	s_waitcnt vmcnt(3)
	ds_write2_b32 v0, v28, v29 offset1:1
	v_add_u32_e32 v0, 0x8208, v73
	ds_write2_b32 v0, v30, v31 offset1:1
	v_add_u32_e32 v0, 0x8200, v74
	s_waitcnt vmcnt(2)
	ds_write2_b32 v0, v24, v25 offset1:1
	v_add_u32_e32 v0, 0x8208, v74
	ds_write2_b32 v0, v26, v27 offset1:1
	v_add_u32_e32 v0, 0xc300, v73
	s_waitcnt vmcnt(1)
	ds_write2_b32 v0, v44, v45 offset1:1
	v_add_u32_e32 v0, 0xc308, v73
	ds_write2_b32 v0, v46, v47 offset1:1
	v_add_u32_e32 v0, 0xc300, v74
	s_waitcnt vmcnt(0)
	ds_write2_b32 v0, v40, v41 offset1:1
	v_add_u32_e32 v0, 0xc308, v74
	ds_write2_b32 v0, v42, v43 offset1:1
	s_branch .Ltr_join
.LBB0_56:
	v_add_u32_e32 v0, 0xc200, v72
	v_add_u32_e32 v2, 0xc400, v72
	v_add_u32_e32 v4, 0xc600, v72
	ds_read2_b32 v[0:1], v0 offset0:64 offset1:129
	ds_read2_b32 v[2:3], v2 offset0:66 offset1:131
	ds_read2_b32 v[4:5], v4 offset0:68 offset1:133
	v_add_u32_e32 v6, 0xc800, v72
	ds_read2_b32 v[6:7], v6 offset0:70 offset1:135
	s_waitcnt lgkmcnt(3)
	v_cvt_pk_bf16_f32 v0, v0, v1
	s_waitcnt lgkmcnt(2)
	v_cvt_pk_bf16_f32 v1, v2, v3
	s_waitcnt lgkmcnt(1)
	v_cvt_pk_bf16_f32 v2, v4, v5
	v_lshl_add_u64 v[4:5], s[6:7], 0, v[66:67]
	v_mov_b32_e32 v71, v67
	s_waitcnt lgkmcnt(0)
	v_cvt_pk_bf16_f32 v3, v6, v7
	v_lshl_add_u64 v[4:5], v[4:5], 0, v[70:71]
	global_store_dwordx4 v[4:5], v[0:3], off
	s_add_i32 s12, s12, s13
	s_add_i32 s14, s14, s15
	s_add_i32 s16, s16, s17
	s_andn2_b64 vcc, exec, s[4:5]
	s_mov_b32 s0, s18
	s_waitcnt vmcnt(4)
	v_mov_b64_e32 v[0:1], v[16:17]
	v_mov_b64_e32 v[2:3], v[18:19]
	v_mov_b64_e32 v[4:5], v[20:21]
	v_mov_b64_e32 v[6:7], v[22:23]
	v_mov_b64_e32 v[12:13], v[32:33]
	v_mov_b64_e32 v[14:15], v[34:35]
	v_mov_b64_e32 v[8:9], v[36:37]
	v_mov_b64_e32 v[10:11], v[38:39]
	v_mov_b64_e32 v[28:29], v[48:49]
	v_mov_b64_e32 v[30:31], v[50:51]
	v_mov_b64_e32 v[24:25], v[52:53]
	v_mov_b64_e32 v[26:27], v[54:55]
	v_mov_b64_e32 v[44:45], v[56:57]
	v_mov_b64_e32 v[46:47], v[58:59]
	v_mov_b64_e32 v[40:41], v[60:61]
	v_mov_b64_e32 v[42:43], v[62:63]
	s_cbranch_vccz .LBB0_123

.LBB0_91:
	s_waitcnt lgkmcnt(0)
	s_barrier
	s_waitcnt vmcnt(15)
	ds_write2_b32 v73, v0, v1 offset1:1
	ds_write2_b32 v73, v2, v3 offset0:2 offset1:3
	s_waitcnt vmcnt(14)
	ds_write2_b32 v74, v4, v5 offset1:1
	ds_write2_b32 v74, v6, v7 offset0:2 offset1:3
	v_add_u32_e32 v0, 0x4100, v73
	s_waitcnt vmcnt(13)
	ds_write2_b32 v0, v12, v13 offset1:1
	v_add_u32_e32 v0, 0x4108, v73
	ds_write2_b32 v0, v14, v15 offset1:1
	v_add_u32_e32 v0, 0x4100, v74
	s_waitcnt vmcnt(12)
	ds_write2_b32 v0, v8, v9 offset1:1
	v_add_u32_e32 v0, 0x4108, v74
	ds_write2_b32 v0, v10, v11 offset1:1
	v_add_u32_e32 v0, 0x8200, v73
	s_waitcnt vmcnt(11)
	ds_write2_b32 v0, v28, v29 offset1:1
	v_add_u32_e32 v0, 0x8208, v73
	ds_write2_b32 v0, v30, v31 offset1:1
	v_add_u32_e32 v0, 0x8200, v74
	s_waitcnt vmcnt(10)
	ds_write2_b32 v0, v24, v25 offset1:1
	v_add_u32_e32 v0, 0x8208, v74
	ds_write2_b32 v0, v26, v27 offset1:1
	v_add_u32_e32 v0, 0xc300, v73
	s_waitcnt vmcnt(9)
	ds_write2_b32 v0, v44, v45 offset1:1
	v_add_u32_e32 v0, 0xc308, v73
	ds_write2_b32 v0, v46, v47 offset1:1
	v_add_u32_e32 v0, 0xc300, v74
	s_waitcnt vmcnt(8)
	ds_write2_b32 v0, v40, v41 offset1:1
	v_add_u32_e32 v0, 0xc308, v74
	ds_write2_b32 v0, v42, v43 offset1:1
.Ltr_join:
	s_waitcnt lgkmcnt(0)
	s_barrier
	s_and_b32 s10, s16, 0x7fffffc0
	s_and_b32 s2, s16, 0x3fc0
	s_cmpk_gt_i32 s0, 0x17ff
	s_mov_b64 s[8:9], -1
	s_cbranch_scc0 .LBB0_97
	s_and_b32 s11, s14, 0x700000
	s_cmpk_gt_u32 s0, 0x1bff
	s_cbranch_scc0 .LBB0_94
	s_add_u32 s6, s40, s11
	s_addc_u32 s7, s41, 0
	s_lshl_b32 s8, s10, 1
	s_add_u32 s6, s6, s8
	s_addc_u32 s7, s7, 0
	s_add_u32 s6, s6, 0xffff9000
	s_addc_u32 s7, s7, -1
	s_mov_b64 s[8:9], 0
